# v23 + HGRN pass 2: the four dwordx2 gate-row loads per chunk widened to two dwordx4 + v_permlane16_swap, store/load column shift folded into the per-item lane constants
# speedup vs baseline: 1.0008x; 1.0008x over previous
; #define LAS __attribute__((address_space(3)))
; template <bool FULL>
; __device__ __forceinline__ void hgrn_pass(int wv, const Args& a, int l, LAS unsigned char* lds, int item, bool dmy) {
;     ...
;     const int b = item >> 6, h = (item >> 3) & 7, p = item & 7;
;     const size_t row_base = (size_t)b * SEQ + (size_t)p * 1024;
;     const bf16_t* HQ = (const bf16_t*)(a.ws + WS_HQ); const bf16_t* HF = (const bf16_t*)(a.ws + WS_HF); const bf16_t* HI = (const bf16_t*)(a.ws + WS_HI); const bf16_t* HGt = (const bf16_t*)(a.ws + WS_HG);
;     bf16_t* OA = dmy ? (bf16_t*)(a.ws + WS_DUMMY) - (size_t)(b * SEQ + p * 1024) * DM : (bf16_t*)a.out;
;     float* US = (float*)(a.ws + WS_US); float* DT = (float*)(a.ws + WS_DT);
;     float lb = 0.f;
;     if (l == 1) { const float l0 = a.in[6][h * 128 + ch], l1 = a.in[6][DM + h * 128 + ch]; lb = 1.f / (1.f + expf(l0 - l1)); }
;     const float oml = 1.f - lb;
;     LAS float* TOT = (LAS float*)(lds + HG_TOT); LAS float* DV = (LAS float*)(lds + HG_DV); LAS float* SSQP = (LAS float*)(lds + HG_SSQP); LAS float* EM = (LAS float*)(lds + HG_EM);
;     const int ti = wid & 3, dvh = wid >> 2;
;     f32x4 sacc[8];
; #pragma unroll
;     for (int j = 0; j < 8; ++j) sacc[j] = (f32x4){0.f, 0.f, 0.f, 0.f};
;     float gsum = 0.f;
;     if (FULL) {
;         for (int pp = 0; pp < p; ++pp) {
;             const int it2 = item - p + pp;
;             const f32x4 dd = *(const f32x4*)(DT + (size_t)it2 * 128 + wid * 16 + 4 * fq);
; #pragma unroll
;             for (int j = 0; j < 8; ++j)
; #pragma unroll
;                 for (int r = 0; r < 4; ++r) sacc[j][r] = sacc[j][r] * dd[r] + US[((size_t)it2 * 128 + wid * 16 + 4 * fq + r) * 128 + j * 16 + fr];
;         }
;     }
;     const unsigned gcol = (unsigned)(h * 128 + ch);
;     unsigned cHF[8], cHI[8], cHQ[8];
;     ...
;     HG_LOAD(cHF, cHI, cHQ, 0);
.LBB0_473:
	s_ashr_i32 s9, s10, 7
	s_waitcnt lgkmcnt(0)
	s_add_u32 s40, s26, 0xc100000
	s_addc_u32 s41, s27, 0
	s_add_u32 s42, s26, 0x10100000
	s_addc_u32 s43, s27, 0
	s_add_u32 s45, s26, 0x14100000
	s_addc_u32 s46, s27, 0
	s_lshl_b32 s7, s9, 4
	s_ashr_i32 s0, s7, 31
	v_readlane_b32 s52, v253, 9
	v_readlane_b32 s53, v253, 10
	s_add_u32 s28, s52, s7
	s_addc_u32 s29, s53, s0
	s_lshl_b64 s[4:5], s[28:29], 11
	s_add_u32 s0, s42, s4
	s_addc_u32 s1, s43, s5
	s_add_u32 s2, s45, s4
	s_addc_u32 s3, s46, s5
	s_add_u32 s4, s40, s4
	s_addc_u32 s5, s41, s5
	s_add_u32 s12, s0, 0x1000
	s_addc_u32 s13, s1, 0
	s_add_u32 s14, s2, 0x1000
	s_addc_u32 s15, s3, 0
	s_add_u32 s16, s4, 0x1000
	s_addc_u32 s17, s5, 0
	s_add_u32 s18, s0, 0x2000
	s_addc_u32 s19, s1, 0
	s_add_u32 s20, s2, 0x2000
	s_addc_u32 s21, s3, 0
	v_or_b32_e32 v46, 0x400, v40
	s_add_u32 s22, s4, 0x2000
	v_lshlrev_b32_e32 v32, 1, v40
	v_lshlrev_b32_e32 v33, 1, v46
	s_addc_u32 s23, s5, 0
	global_load_ushort v34, v32, s[0:1]
	global_load_ushort v35, v32, s[0:1] offset:2048
	global_load_ushort v36, v32, s[2:3]
	global_load_ushort v37, v32, s[2:3] offset:2048
	global_load_ushort v38, v32, s[4:5]
	global_load_ushort v39, v32, s[4:5] offset:2048
	global_load_ushort v43, v32, s[12:13]
	global_load_ushort v50, v32, s[14:15]
	global_load_ushort v51, v33, s[12:13]
	global_load_ushort v52, v33, s[14:15]
	global_load_ushort v53, v33, s[16:17]
	global_load_ushort v54, v33, s[18:19]
	global_load_ushort v55, v33, s[20:21]
	s_add_u32 s12, s0, 0x3000
	s_addc_u32 s13, s1, 0
	s_add_u32 s14, s2, 0x3000
	s_addc_u32 s15, s3, 0
	s_add_u32 s36, s4, 0x3000
	s_addc_u32 s37, s5, 0
	s_add_u32 s38, s0, 0x4000
	s_addc_u32 s39, s1, 0
	s_add_u32 s48, s2, 0x4000
	s_addc_u32 s49, s3, 0
	s_add_u32 s50, s4, 0x4000
	s_addc_u32 s51, s5, 0
	global_load_ushort v56, v32, s[16:17]
	global_load_ushort v57, v32, s[18:19]
	global_load_ushort v58, v32, s[20:21]
	global_load_ushort v59, v32, s[22:23]
	global_load_ushort v60, v32, s[12:13]
	global_load_ushort v61, v32, s[14:15]
	global_load_ushort v62, v32, s[36:37]
	global_load_ushort v63, v32, s[38:39]
	s_add_u32 s16, s0, 0x5000
	s_addc_u32 s17, s1, 0
	s_add_u32 s18, s2, 0x5000
	s_addc_u32 s19, s3, 0
	s_add_u32 s20, s4, 0x5000
	s_addc_u32 s21, s5, 0
	global_load_ushort v64, v33, s[22:23]
	global_load_ushort v65, v33, s[12:13]
	global_load_ushort v66, v33, s[14:15]
	global_load_ushort v67, v33, s[36:37]
	global_load_ushort v68, v33, s[38:39]
	global_load_ushort v69, v33, s[48:49]
	global_load_ushort v70, v33, s[50:51]
	global_load_ushort v71, v33, s[16:17]
	s_add_u32 s12, s0, 0x6000
	s_addc_u32 s13, s1, 0
	s_add_u32 s14, s2, 0x6000
	s_addc_u32 s15, s3, 0
	s_add_u32 s22, s4, 0x6000
	s_addc_u32 s23, s5, 0
	s_add_u32 s0, s0, 0x7000
	s_addc_u32 s1, s1, 0
	global_load_ushort v73, v32, s[48:49]
	global_load_ushort v74, v32, s[50:51]
	global_load_ushort v75, v32, s[16:17]
	global_load_ushort v76, v32, s[18:19]
	global_load_ushort v77, v32, s[20:21]
	global_load_ushort v78, v32, s[12:13]
	global_load_ushort v79, v32, s[14:15]
	global_load_ushort v80, v32, s[22:23]
	s_add_u32 s2, s2, 0x7000
	s_addc_u32 s3, s3, 0
	s_add_u32 s4, s4, 0x7000
	s_addc_u32 s5, s5, 0
	global_load_ushort v81, v32, s[0:1]
	global_load_ushort v82, v32, s[2:3]
	global_load_ushort v83, v32, s[4:5]
	global_load_ushort v84, v33, s[18:19]
	global_load_ushort v85, v33, s[20:21]
	global_load_ushort v86, v33, s[12:13]
	global_load_ushort v87, v33, s[14:15]
	global_load_ushort v89, v33, s[22:23]
	global_load_ushort v90, v33, s[0:1]
	global_load_ushort v91, v33, s[2:3]
	global_load_ushort v92, v33, s[4:5]
	s_and_b32 s0, s10, 0x3fffff80
	s_lshl_b32 s0, s0, 2
	s_add_i32 s0, s69, s0
	v_lshlrev_b32_e32 v96, 2, v41
	s_cmp_gt_i32 s9, 0
	v_lshlrev_b32_e32 v48, 2, v48
	s_movk_i32 s49, 0x88
	v_readlane_b32 s13, v253, 24
	v_sub_f32_e32 v72, 1.0, v88
	s_mov_b32 s47, 64
	v_add_u32_e32 v95, 0, v96
	v_lshlrev_b32_e32 v117, 1, v40
	v_lshlrev_b32_e32 v118, 1, v46
	s_waitcnt vmcnt(46)
	v_lshl_or_b32 v228, v35, 16, v34
	s_waitcnt vmcnt(44)
	v_lshl_or_b32 v32, v37, 16, v36
	s_waitcnt vmcnt(42)
	v_lshl_or_b32 v181, v39, 16, v38
	s_waitcnt vmcnt(39)
	v_lshl_or_b32 v223, v51, 16, v43
	s_waitcnt vmcnt(38)
	v_lshl_or_b32 v33, v52, 16, v50
	v_mul_u32_u24_e32 v50, 0x48, v41
	v_add_u32_e32 v43, 0x88, v41
	v_or_b32_e32 v52, s7, v47
	v_mul_lo_u32 v52, v52, s49
	s_waitcnt vmcnt(34)
	v_lshl_or_b32 v180, v53, 16, v56
	s_waitcnt vmcnt(33)
	v_lshl_or_b32 v222, v54, 16, v57
	v_lshlrev_b32_e32 v53, 3, v49
	v_or_b32_e32 v54, s7, v42
	s_waitcnt vmcnt(32)
	v_lshl_or_b32 v34, v55, 16, v58
	v_mul_lo_u32 v58, v54, s55
	v_or_b32_e32 v55, 1, v54
	s_waitcnt vmcnt(26)
	v_lshl_or_b32 v179, v64, 16, v59
	s_waitcnt vmcnt(25)
	v_lshl_or_b32 v236, v65, 16, v60
	v_bfrev_b32_e32 v65, 0.5
	v_bitop3_b32 v93, v48, s54, v65 bitop3:0x6c
	s_waitcnt vmcnt(22)
	v_lshl_or_b32 v242, v68, 16, v63
	v_lshl_or_b32 v178, v67, 16, v62
	v_lshl_or_b32 v35, v66, 16, v61
	v_or_b32_e32 v56, 2, v54
	v_or_b32_e32 v57, 3, v54
	s_waitcnt vmcnt(18)
	v_lshl_or_b32 v36, v69, 16, v73
	s_waitcnt vmcnt(17)
	v_lshl_or_b32 v177, v70, 16, v74
	s_waitcnt vmcnt(16)
	v_lshl_or_b32 v199, v71, 16, v75
	v_add_u32_e32 v59, 0x48, v58
	v_add_u32_e32 v60, 0x90, v58
	s_waitcnt vmcnt(7)
	v_lshl_or_b32 v37, v84, 16, v76
	s_waitcnt vmcnt(6)
	v_lshl_or_b32 v176, v85, 16, v77
	v_add_u32_e32 v61, 0xd8, v58
	s_waitcnt vmcnt(4)
	v_lshl_or_b32 v38, v87, 16, v79
	s_waitcnt vmcnt(3)
	v_lshl_or_b32 v175, v89, 16, v80
	v_add_u32_e32 v89, s0, v96
	s_cselect_b64 s[0:1], -1, 0
	s_cmp_gt_i32 s9, 1
	s_cselect_b64 s[2:3], -1, 0
	s_cmp_gt_i32 s9, 2
	s_cselect_b64 s[4:5], -1, 0
	s_cmpk_lt_u32 s10, 0x80
	s_waitcnt vmcnt(1)
	v_lshl_or_b32 v39, v91, 16, v82
	s_waitcnt vmcnt(0)
; #define LAS __attribute__((address_space(3)))
; __device__ __forceinline__ unsigned pk2(float lo, float hi) { f32x2 v = {lo, hi}; bf2_t b = __builtin_convertvector(v, bf2_t); return __builtin_bit_cast(unsigned, b); }
; __device__ __forceinline__ f32x4 mfma16(bf16x8 a, bf16x8 b, f32x4 c) { return __builtin_amdgcn_mfma_f32_16x16x32_bf16(a, b, c, 0, 0, 0); }
; template <bool FULL>
; __device__ __forceinline__ void hgrn_pass(int wv, const Args& a, int l, LAS unsigned char* lds, int item, bool dmy) {
;     ...
;                 const int tiA = wid >> 1;
; #pragma unroll
;                 for (int q = 0; q < 2; ++q) {
;                     const int sj = (wid & 1) * 2 + q;
;                     f32x4 ac = (f32x4){0.f, 0.f, 0.f, 0.f};
; #pragma unroll
;                     for (int k4 = 0; k4 < 4; ++k4) {
;                         const bf16x8 av = lds_ld16(lds + HG_QH + ((tiA * 16 + fr) * 136 + k4 * 32 + 8 * fq) * 2);
;                         const bf16x8 bv = lds_ld16(lds + HG_KH + ((sj * 16 + fr) * 136 + k4 * 32 + 8 * fq) * 2);
;                         ac = mfma16(av, bv, ac);
;                     }
;                     const int s = sj * 16 + fr, tb0 = tiA * 16 + 4 * fq;
;                     const unsigned w0 = pk2(s <= tb0 ? ac[0] : 0.f, s <= tb0 + 1 ? ac[1] : 0.f), w1 = pk2(s <= tb0 + 2 ? ac[2] : 0.f, s <= tb0 + 3 ? ac[3] : 0.f);
;                     *(LAS bf16_t*)(lds + HG_AM + ((tb0 + 0) * 72 + s) * 2) = (bf16_t)(w0 & 0xffffu);
;                     *(LAS bf16_t*)(lds + HG_AM + ((tb0 + 1) * 72 + s) * 2) = (bf16_t)(w0 >> 16);
;                     *(LAS bf16_t*)(lds + HG_AM + ((tb0 + 2) * 72 + s) * 2) = (bf16_t)(w1 & 0xffffu);
;                     *(LAS bf16_t*)(lds + HG_AM + ((tb0 + 3) * 72 + s) * 2) = (bf16_t)(w1 >> 16);
;                 }
;             }
;             __syncthreads();
;             { const size_t or_ = row_base + (size_t)c * 64 + ti * 16 + fr;
; #pragma unroll
;               for (int jj = 0; jj < 4; ++jj) { cHG[jj] = *(const u32x2*)(HGt + or_ * DM + h * 128 + (dvh * 4 + jj) * 16 + 4 * fq); gn[jj] = *(const f32x4*)(a.in[7] + l * DM + h * 128 + (dvh * 4 + jj) * 16 + 4 * fq); } }
	v_lshl_or_b32 v174, v92, 16, v83
	s_cselect_b64 s[36:37], -1, 0
	v_add_lshl_u32 v91, v50, s7, 1
	v_or_b32_e32 v50, s8, v42
	s_and_b32 s12, s8, 48
	v_bitop3_b32 v92, v48, 64, v65 bitop3:0x6c
	v_or_b32_e32 v48, s8, v47
	s_mul_i32 s8, s9, 0x880
	s_add_i32 s9, s8, 0x110
	v_add_lshl_u32 v68, s9, v41, 1
	v_add_lshl_u32 v69, s9, v43, 1
	s_add_i32 s9, s8, 0x220
	v_add_lshl_u32 v70, s9, v41, 1
	v_add_lshl_u32 v71, s9, v43, 1
	s_add_i32 s9, s8, 0x330
	v_lshl_or_b32 v182, v90, 16, v81
	v_add_lshl_u32 v80, s9, v41, 1
	v_add_lshl_u32 v81, s9, v43, 1
	s_add_i32 s9, s8, 0x440
	s_lshl_b32 s11, s6, 5
	s_ashr_i32 s6, s10, 2
	v_add_lshl_u32 v82, s9, v41, 1
	v_add_lshl_u32 v83, s9, v43, 1
	s_add_i32 s9, s8, 0x550
	s_and_b32 s38, s6, 0xffffffc0
	v_cmp_eq_u32_e64 s[6:7], 0, v49
	v_or_b32_e32 v49, s8, v41
	v_add_lshl_u32 v67, v43, s8, 1
	v_add_lshl_u32 v84, s9, v41, 1
	v_add_lshl_u32 v85, s9, v43, 1
	s_add_i32 s9, s8, 0x660
	s_addk_i32 s8, 0x770
	v_or_b32_e32 v188, s12, v47
	s_lshl_b32 s12, s12, 2
	v_add_lshl_u32 v87, s9, v43, 1
	v_add_lshl_u32 v134, s8, v43, 1
	v_mul_u32_u24_e32 v43, 0x88, v47
	s_add_i32 s12, s13, s12
	v_add_lshl_u32 v97, v50, v43, 1
	v_and_or_b32 v43, s11, 32, v47
	v_lshl_or_b32 v183, v86, 16, v78
	v_lshlrev_b32_e32 v51, 2, v50
	v_or_b32_e32 v63, s38, v47
	v_lshl_add_u32 v65, v47, 2, s12
	v_lshl_add_u32 v94, v188, 2, s13
	s_and_b32 s48, s10, 0xffffff00
	v_lshlrev_b32_e32 v66, 1, v49
	v_add_lshl_u32 v86, s9, v41, 1
	v_add_lshl_u32 v41, s8, v41, 1
	v_add_lshl_u32 v50, v52, v53, 1
	v_mul_u32_u24_e32 v49, 0x88, v43
	v_cmp_gt_i32_e64 s[8:9], v43, v54
	v_cmp_gt_i32_e64 s[10:11], v43, v55
	v_cmp_gt_i32_e64 s[12:13], v43, v56
	v_cmp_gt_i32_e64 s[14:15], v43, v57
	v_add_lshl_u32 v52, v58, v43, 1
	v_add_lshl_u32 v137, v59, v43, 1
	v_add_lshl_u32 v138, v60, v43, 1
	v_add_lshl_u32 v139, v61, v43, 1
	v_or_b32_e32 v43, 16, v43
	v_cmp_gt_i32_e64 s[16:17], v43, v54
	v_cmp_gt_i32_e64 s[18:19], v43, v55
	v_cmp_gt_i32_e64 s[20:21], v43, v56
	v_cmp_gt_i32_e64 s[22:23], v43, v57
	v_add_lshl_u32 v54, v58, v43, 1
	v_add_lshl_u32 v55, v59, v43, 1
	v_add_lshl_u32 v56, v60, v43, 1
	v_add_lshl_u32 v57, v61, v43, 1
	v_mul_lo_u32 v43, v63, s55
	v_or_b32_e32 v74, 32, v53
	v_mad_u32_u24 v62, v188, s55, v53
	v_lshlrev_b32_e32 v64, 6, v188
	v_add_lshl_u32 v100, v49, v53, 1
	s_ashr_i32 s39, s38, 31
	v_add_lshl_u32 v59, v43, v53, 1
	v_add_u32_e32 v49, 0x480, v43
	v_add_u32_e32 v61, 0x900, v43
	v_add_u32_e32 v73, 0xd80, v43
	v_add_lshl_u32 v154, v43, v74, 1
	v_mul_lo_u32 v43, v63, s49
	s_lshl_b64 s[34:35], s[34:35], 2
	v_lshlrev_b32_e32 v58, 1, v62
	v_add_lshl_u32 v60, v49, v53, 1
	v_add_lshl_u32 v153, v73, v53, 1
	v_add_lshl_u32 v155, v49, v74, 1
	v_add_lshl_u32 v157, v73, v74, 1
	v_add_lshl_u32 v62, v62, v64, 1
	v_add_u32_e32 v49, 0x880, v43
	v_add_u32_e32 v63, 0x1100, v43
	v_add_u32_e32 v64, 0x1980, v43
	v_or_b32_e32 v73, 64, v53
	s_add_u32 s30, s30, s34
	v_mul_lo_u32 v48, v48, s55
	v_add_lshl_u32 v109, v43, v73, 1
	v_add_lshl_u32 v110, v49, v73, 1
	v_add_lshl_u32 v111, v63, v73, 1
	v_add_lshl_u32 v112, v64, v73, 1
	v_or_b32_e32 v73, 0x60, v53
	s_addc_u32 s31, s31, s35
	s_lshl_b32 s34, s59, 2
	v_add_lshl_u32 v102, v49, v53, 1
	v_add_lshl_u32 v103, v63, v53, 1
	v_add_lshl_u32 v106, v49, v74, 1
	v_add_lshl_u32 v107, v63, v74, 1
	v_add_lshl_u32 v114, v49, v73, 1
	v_add_lshl_u32 v115, v63, v73, 1
	v_add_lshl_u32 v63, v48, v53, 1
	v_mov_b32_e32 v48, 0x480
	v_mov_b32_e32 v49, 0x900
	s_add_u32 s30, s30, s34
	v_mad_u32_u24 v48, v47, s55, v48
	v_mad_u32_u24 v49, v47, s55, v49
	s_addc_u32 s31, s31, 0
	v_add_lshl_u32 v113, v43, v73, 1
	v_add_lshl_u32 v116, v64, v73, 1
	v_add_lshl_u32 v159, v53, v48, 1
	v_add_lshl_u32 v160, v53, v49, 1
	v_mov_b32_e32 v73, 0xd80
	v_mov_b32_e32 v75, 0x1200
	v_mov_b32_e32 v76, 0x1680
	v_mov_b32_e32 v77, 0x1b00
	v_mov_b32_e32 v78, 0x1f80
	v_add_lshl_u32 v167, v74, v48, 1
	v_add_lshl_u32 v168, v74, v49, 1
	v_lshl_add_u64 v[48:49], v[44:45], 2, s[30:31]
	v_readlane_b32 s30, v253, 20
	v_add_lshl_u32 v101, v43, v53, 1
	v_add_lshl_u32 v105, v43, v74, 1
	v_mul_u32_u24_e32 v43, 0x48, v47
	v_mad_u32_u24 v73, v47, s55, v73
	v_mad_u32_u24 v75, v47, s55, v75
	v_mad_u32_u24 v76, v47, s55, v76
	v_mad_u32_u24 v77, v47, s55, v77
	v_mad_u32_u24 v47, v47, s55, v78
	s_add_u32 s30, s26, s30
	v_add_lshl_u32 v152, v61, v53, 1
	v_add_lshl_u32 v61, v61, v74, 1
	v_add_lshl_u32 v104, v64, v53, 1
	v_add_lshl_u32 v108, v64, v74, 1
	v_add_lshl_u32 v64, v53, v43, 1
	v_add_lshl_u32 v161, v53, v73, 1
	v_add_lshl_u32 v162, v53, v75, 1
	v_add_lshl_u32 v163, v53, v76, 1
	v_add_lshl_u32 v164, v53, v77, 1
	v_add_lshl_u32 v53, v53, v47, 1
	v_add_lshl_u32 v166, v74, v43, 1
	v_add_lshl_u32 v169, v74, v73, 1
	v_add_lshl_u32 v170, v74, v75, 1
	v_add_lshl_u32 v171, v74, v76, 1
	v_add_lshl_u32 v172, v74, v77, 1
	v_add_lshl_u32 v47, v74, v47, 1
	v_lshl_add_u64 v[74:75], s[38:39], 2, v[48:49]
	s_addc_u32 s31, s27, 0
	v_lshl_add_u64 v[48:49], s[52:53], 0, v[188:189]
	s_lshl_b64 s[26:27], s[38:39], 1
	v_lshlrev_b64 v[48:49], 11, v[48:49]
	s_add_u32 s26, s30, s26
	v_lshl_add_u64 v[44:45], v[44:45], 1, v[48:49]
	s_addc_u32 s27, s31, s27
	v_lshl_add_u64 v[76:77], s[26:27], 0, v[44:45]
	v_readlane_b32 s26, v253, 19
	v_add_u32_e32 v42, s38, v42
	s_add_u32 s24, s24, s26
	v_ashrrev_i32_e32 v43, 31, v42
	s_addc_u32 s25, s25, 0
	v_lshl_add_u64 v[42:43], v[42:43], 1, v[48:49]
	v_add_u32_e32 v140, 0x1100, v100
	v_lshl_add_u64 v[78:79], s[24:25], 0, v[42:43]
	v_mbcnt_lo_u32_b32 v42, -1, 0
	v_mbcnt_hi_u32_b32 v42, -1, v42
	v_bfe_u32 v42, v42, 4, 1
	v_mul_u32_u24_e32 v42, 24, v42
	v_mov_b32_e32 v43, 0
	v_lshl_add_u64 v[76:77], v[42:43], 0, v[76:77]
	v_lshl_add_u64 v[78:79], v[42:43], 0, v[78:79]
	v_readlane_b32 s24, v253, 25
; #define LAS __attribute__((address_space(3)))
; __device__ __forceinline__ f32x4 mfma16(bf16x8 a, bf16x8 b, f32x4 c) { return __builtin_amdgcn_mfma_f32_16x16x32_bf16(a, b, c, 0, 0, 0); }
; template <bool FULL>
; __device__ __forceinline__ void hgrn_pass(int wv, const Args& a, int l, LAS unsigned char* lds, int item, bool dmy) {
;     ...
;         {
;             const f32x4 dd = *(const LAS f32x4*)(lds + HG_DV + (wid * 16 + 4 * fq) * 4);
; #pragma unroll
;             for (int j = 0; j < 8; ++j) sacc[j] = sacc[j] * dd;
; #pragma unroll
;             for (int k2 = 0; k2 < 2; ++k2) {
;                 const bf16x8 av = lds_ld16(lds + HG_KTT + ((wid * 16 + fr) * 72 + k2 * 32 + 8 * fq) * 2);
; #pragma unroll
;                 for (int j = 0; j < 8; ++j) { const bf16x8 bv = lds_ld16(lds + HG_VTT + ((j * 16 + fr) * 72 + k2 * 32 + 8 * fq) * 2); sacc[j] = mfma16(av, bv, sacc[j]); }
;             }
;         }
	v_add_u32_e32 v90, s69, v96
	v_add_u32_e32 v96, s70, v96
	v_add_u32_e32 v98, 0x6600, v97
	v_add_u32_e32 v99, 0x7700, v97
	v_mov_b32_e32 v73, v72
	s_mov_b64 s[26:27], 0
	v_add_u32_e32 v119, 0, v66
	v_add_u32_e32 v120, 0, v67
	v_add_u32_e32 v121, 0, v68
	v_add_u32_e32 v122, 0, v69
	v_add_u32_e32 v123, 0, v70
	v_add_u32_e32 v124, 0, v71
	v_add_u32_e32 v125, 0, v80
	v_add_u32_e32 v126, 0, v81
	v_add_u32_e32 v127, 0, v82
	v_add_u32_e32 v128, 0, v83
	v_add_u32_e32 v129, 0, v84
	v_add_u32_e32 v130, 0, v85
	v_add_u32_e32 v131, 0, v86
	v_add_u32_e32 v132, 0, v87
	v_add_u32_e32 v133, 0, v41
	v_add_u32_e32 v134, 0, v134
	v_add_u32_e32 v135, 0, v50
	v_add_u32_e32 v136, s24, v52
	v_add_u32_e32 v137, s24, v137
	v_add_u32_e32 v138, s24, v138
	v_add_u32_e32 v139, s24, v139
	v_add_u32_e32 v140, 0, v140
	v_add_u32_e32 v141, s24, v54
	v_add_u32_e32 v142, s24, v55
	v_add_u32_e32 v143, s24, v56
	v_add_u32_e32 v144, s24, v57
	v_add_u32_e32 v145, s24, v58
	v_add_u32_e32 v146, 0, v62
	v_add_u32_e32 v147, s48, v65
	v_add_u32_e32 v148, 0, v63
	v_add_u32_e32 v149, 0, v51
	v_add_u32_e32 v150, s71, v59
	v_add_u32_e32 v151, s71, v60
	v_add_u32_e32 v152, s71, v152
	v_add_u32_e32 v153, s71, v153
	v_add_u32_e32 v154, s71, v154
	v_add_u32_e32 v155, s71, v155
	v_add_u32_e32 v156, s71, v61
	v_add_u32_e32 v157, s71, v157
	v_add_u32_e32 v158, s71, v64
	v_add_u32_e32 v159, s71, v159
	v_add_u32_e32 v160, s71, v160
	v_add_u32_e32 v161, s71, v161
	v_add_u32_e32 v162, s71, v162
	v_add_u32_e32 v163, s71, v163
	v_add_u32_e32 v164, s71, v164
	v_add_u32_e32 v165, s71, v53
	v_add_u32_e32 v166, s71, v166
	v_add_u32_e32 v167, s71, v167
	v_add_u32_e32 v168, s71, v168
	v_add_u32_e32 v169, s71, v169
	v_add_u32_e32 v170, s71, v170
	v_add_u32_e32 v171, s71, v171
	v_add_u32_e32 v172, s71, v172
	v_add_u32_e32 v173, s71, v47
	s_branch .LBB0_475
.LBB0_474:
	s_or_b64 exec, exec, s[24:25]
	s_waitcnt vmcnt(52)
	v_lshlrev_b32_e32 v32, 16, v187
	v_or_b32_sdwa v228, v32, v184 dst_sel:DWORD dst_unused:UNUSED_PAD src0_sel:DWORD src1_sel:WORD_0
	s_waitcnt vmcnt(50)
	v_lshlrev_b32_e32 v32, 16, v188
	s_waitcnt vmcnt(48) lgkmcnt(0)
	v_lshlrev_b32_e32 v33, 16, v198
	v_add_u32_e32 v184, 0x21000, v149
	v_or_b32_sdwa v32, v32, v185 dst_sel:DWORD dst_unused:UNUSED_PAD src0_sel:DWORD src1_sel:WORD_0
	v_or_b32_sdwa v181, v33, v186 dst_sel:DWORD dst_unused:UNUSED_PAD src0_sel:DWORD src1_sel:WORD_0
	ds_read_b128 v[184:187], v184
	s_waitcnt vmcnt(46)
	v_lshlrev_b32_e32 v33, 16, v201
	v_or_b32_sdwa v223, v33, v200 dst_sel:DWORD dst_unused:UNUSED_PAD src0_sel:DWORD src1_sel:WORD_0
	s_waitcnt vmcnt(44)
	v_lshlrev_b32_e32 v33, 16, v204
	s_waitcnt vmcnt(42)
	v_lshlrev_b32_e32 v34, 16, v205
	v_or_b32_sdwa v33, v33, v202 dst_sel:DWORD dst_unused:UNUSED_PAD src0_sel:DWORD src1_sel:WORD_0
	v_or_b32_sdwa v180, v34, v203 dst_sel:DWORD dst_unused:UNUSED_PAD src0_sel:DWORD src1_sel:WORD_0
	s_waitcnt lgkmcnt(0)
	v_pk_mul_f32 v[2:3], v[2:3], v[186:187]
	v_pk_mul_f32 v[0:1], v[0:1], v[184:185]
	v_pk_mul_f32 v[6:7], v[6:7], v[186:187]
	v_pk_mul_f32 v[4:5], v[4:5], v[184:185]
	v_pk_mul_f32 v[10:11], v[10:11], v[186:187]
	v_pk_mul_f32 v[8:9], v[8:9], v[184:185]
	v_pk_mul_f32 v[14:15], v[14:15], v[186:187]
	v_pk_mul_f32 v[12:13], v[12:13], v[184:185]
	v_pk_mul_f32 v[18:19], v[18:19], v[186:187]
	v_pk_mul_f32 v[16:17], v[16:17], v[184:185]
	v_pk_mul_f32 v[22:23], v[22:23], v[186:187]
	v_pk_mul_f32 v[20:21], v[20:21], v[184:185]
	v_pk_mul_f32 v[26:27], v[26:27], v[186:187]
	v_pk_mul_f32 v[24:25], v[24:25], v[184:185]
	v_pk_mul_f32 v[30:31], v[30:31], v[186:187]
	v_pk_mul_f32 v[28:29], v[28:29], v[184:185]
	ds_read_b128 v[184:187], v148 offset:52224
	ds_read_b128 v[200:203], v158
	s_waitcnt lgkmcnt(0)
	v_mfma_f32_16x16x32_bf16 v[0:3], v[184:187], v[200:203], v[0:3]
	ds_read_b128 v[200:203], v159
	s_waitcnt vmcnt(36)
	v_lshlrev_b32_e32 v35, 16, v211
	s_waitcnt vmcnt(30)
	v_lshlrev_b32_e32 v36, 16, v217
	s_waitcnt lgkmcnt(0)
	v_mfma_f32_16x16x32_bf16 v[4:7], v[184:187], v[200:203], v[4:7]
	ds_read_b128 v[200:203], v160
	s_waitcnt vmcnt(24)
	v_lshlrev_b32_e32 v37, 16, v240
	s_waitcnt vmcnt(18)
	v_lshlrev_b32_e32 v38, 16, v247
	s_waitcnt lgkmcnt(0)
	v_mfma_f32_16x16x32_bf16 v[8:11], v[184:187], v[200:203], v[8:11]
	ds_read_b128 v[200:203], v161
	s_waitcnt vmcnt(12)
	v_lshlrev_b32_e32 v39, 16, v224
	v_lshlrev_b32_e32 v34, 16, v209
	s_waitcnt lgkmcnt(0)
	v_mfma_f32_16x16x32_bf16 v[12:15], v[184:187], v[200:203], v[12:15]
	ds_read_b128 v[200:203], v162
	v_or_b32_sdwa v179, v35, v208 dst_sel:DWORD dst_unused:UNUSED_PAD src0_sel:DWORD src1_sel:WORD_0
	v_lshlrev_b32_e32 v35, 16, v215
	s_waitcnt lgkmcnt(0)
	v_mfma_f32_16x16x32_bf16 v[16:19], v[184:187], v[200:203], v[16:19]
	ds_read_b128 v[200:203], v163
	v_or_b32_sdwa v178, v36, v214 dst_sel:DWORD dst_unused:UNUSED_PAD src0_sel:DWORD src1_sel:WORD_0
	v_lshlrev_b32_e32 v36, 16, v221
	s_waitcnt lgkmcnt(0)
	v_mfma_f32_16x16x32_bf16 v[20:23], v[184:187], v[200:203], v[20:23]
	ds_read_b128 v[200:203], v164
	v_or_b32_sdwa v177, v37, v220 dst_sel:DWORD dst_unused:UNUSED_PAD src0_sel:DWORD src1_sel:WORD_0
	v_lshlrev_b32_e32 v37, 16, v245
	s_waitcnt lgkmcnt(0)
	v_mfma_f32_16x16x32_bf16 v[24:27], v[184:187], v[200:203], v[24:27]
	ds_read_b128 v[200:203], v165
	v_or_b32_sdwa v176, v38, v244 dst_sel:DWORD dst_unused:UNUSED_PAD src0_sel:DWORD src1_sel:WORD_0
	v_lshlrev_b32_e32 v38, 16, v249
	s_waitcnt lgkmcnt(0)
	v_mfma_f32_16x16x32_bf16 v[28:31], v[184:187], v[200:203], v[28:31]
	ds_read_b128 v[184:187], v148 offset:52288
	ds_read_b128 v[200:203], v166
	v_or_b32_sdwa v175, v39, v229 dst_sel:DWORD dst_unused:UNUSED_PAD src0_sel:DWORD src1_sel:WORD_0
	s_waitcnt vmcnt(10)
	v_lshlrev_b32_e32 v39, 16, v233
	s_waitcnt lgkmcnt(0)
; __device__ __forceinline__ float bflo(unsigned u) { return __uint_as_float(u << 16); }
; __device__ __forceinline__ float bfhi(unsigned u) { return __uint_as_float(u & 0xffff0000u); }
; __device__ __forceinline__ unsigned pk2(float lo, float hi) { f32x2 v = {lo, hi}; bf2_t b = __builtin_convertvector(v, bf2_t); return __builtin_bit_cast(unsigned, b); }
; template <bool FULL>
; __device__ __forceinline__ void hgrn_pass(int wv, const Args& a, int l, LAS unsigned char* lds, int item, bool dmy) {
;     ...
;         __syncthreads();
;         if (FULL) {
;             const int t = ti * 16 + fr;
;             const float tot = SSQP[t] + SSQP[64 + t];
;             const float rs = rsqrtf(tot * (1.f / 128.f) + EPS);
;             const size_t orow = row_base + (size_t)c * 64 + t;
; #pragma unroll
;             for (int jj = 0; jj < 4; ++jj) {
;                 const int dv0 = (dvh * 4 + jj) * 16 + 4 * fq;
;                 const u32x2 hg = cHG[jj];
;                 const float o0 = oacc[jj][0] * rs * gn[jj][0] * bflo(hg.x), o1 = oacc[jj][1] * rs * gn[jj][1] * bfhi(hg.x), o2 = oacc[jj][2] * rs * gn[jj][2] * bflo(hg.y), o3 = oacc[jj][3] * rs * gn[jj][3] * bfhi(hg.y);
;                 u32x2 w; w.x = pk2(o0, o1); w.y = pk2(o2, o3);
;                 *(u32x2*)(OA + orow * DM + h * 128 + dv0) = w;
;             }
	v_mfma_f32_16x16x32_bf16 v[0:3], v[184:187], v[200:203], v[0:3]
	ds_read_b128 v[200:203], v167
	v_or_b32_sdwa v222, v34, v206 dst_sel:DWORD dst_unused:UNUSED_PAD src0_sel:DWORD src1_sel:WORD_0
	v_lshlrev_b32_e32 v34, 16, v210
	s_waitcnt lgkmcnt(0)
	v_mfma_f32_16x16x32_bf16 v[4:7], v[184:187], v[200:203], v[4:7]
	ds_read_b128 v[200:203], v168
	v_or_b32_sdwa v236, v35, v212 dst_sel:DWORD dst_unused:UNUSED_PAD src0_sel:DWORD src1_sel:WORD_0
	v_lshlrev_b32_e32 v35, 16, v216
	s_waitcnt lgkmcnt(0)
	v_mfma_f32_16x16x32_bf16 v[8:11], v[184:187], v[200:203], v[8:11]
	ds_read_b128 v[200:203], v169
	v_or_b32_sdwa v242, v36, v218 dst_sel:DWORD dst_unused:UNUSED_PAD src0_sel:DWORD src1_sel:WORD_0
	v_lshlrev_b32_e32 v36, 16, v239
	s_waitcnt lgkmcnt(0)
	v_mfma_f32_16x16x32_bf16 v[12:15], v[184:187], v[200:203], v[12:15]
	ds_read_b128 v[200:203], v170
	v_or_b32_sdwa v199, v37, v241 dst_sel:DWORD dst_unused:UNUSED_PAD src0_sel:DWORD src1_sel:WORD_0
	v_lshlrev_b32_e32 v37, 16, v246
	s_waitcnt lgkmcnt(0)
	v_mfma_f32_16x16x32_bf16 v[16:19], v[184:187], v[200:203], v[16:19]
	ds_read_b128 v[200:203], v171
	v_or_b32_sdwa v183, v38, v248 dst_sel:DWORD dst_unused:UNUSED_PAD src0_sel:DWORD src1_sel:WORD_0
	v_lshlrev_b32_e32 v38, 16, v251
	s_waitcnt lgkmcnt(0)
	v_mfma_f32_16x16x32_bf16 v[20:23], v[184:187], v[200:203], v[20:23]
	ds_read_b128 v[200:203], v172
	v_or_b32_sdwa v182, v39, v230 dst_sel:DWORD dst_unused:UNUSED_PAD src0_sel:DWORD src1_sel:WORD_0
	s_waitcnt vmcnt(8)
	v_lshlrev_b32_e32 v39, 16, v234
	s_waitcnt lgkmcnt(0)
	v_mfma_f32_16x16x32_bf16 v[24:27], v[184:187], v[200:203], v[24:27]
	ds_read_b128 v[200:203], v173
	s_waitcnt lgkmcnt(0)
	s_barrier
	v_mfma_f32_16x16x32_bf16 v[28:31], v[184:187], v[200:203], v[28:31]
	ds_read2st64_b32 v[184:185], v94 offset1:1
	s_waitcnt vmcnt(6)
	v_lshlrev_b32_e32 v174, 16, v235
	v_or_b32_sdwa v34, v34, v207 dst_sel:DWORD dst_unused:UNUSED_PAD src0_sel:DWORD src1_sel:WORD_0
	v_or_b32_sdwa v35, v35, v213 dst_sel:DWORD dst_unused:UNUSED_PAD src0_sel:DWORD src1_sel:WORD_0
	v_or_b32_sdwa v36, v36, v219 dst_sel:DWORD dst_unused:UNUSED_PAD src0_sel:DWORD src1_sel:WORD_0
	s_waitcnt lgkmcnt(0)
	v_add_f32_e32 v184, v184, v185
	v_fmamk_f32 v184, v184, 0x3c000000, v226
	v_cmp_gt_f32_e32 vcc, s33, v184
	v_mul_f32_e32 v185, 0x4b800000, v184
	v_or_b32_sdwa v37, v37, v243 dst_sel:DWORD dst_unused:UNUSED_PAD src0_sel:DWORD src1_sel:WORD_0
	v_cndmask_b32_e32 v184, v184, v185, vcc
	v_rsq_f32_e32 v184, v184
	v_or_b32_sdwa v38, v38, v250 dst_sel:DWORD dst_unused:UNUSED_PAD src0_sel:DWORD src1_sel:WORD_0
	v_or_b32_sdwa v39, v39, v231 dst_sel:DWORD dst_unused:UNUSED_PAD src0_sel:DWORD src1_sel:WORD_0
	v_or_b32_sdwa v174, v174, v232 dst_sel:DWORD dst_unused:UNUSED_PAD src0_sel:DWORD src1_sel:WORD_0
	v_mul_f32_e32 v185, 0x45800000, v184
	v_cndmask_b32_e32 v184, v184, v185, vcc
	v_pk_mul_f32 v[64:65], v[64:65], v[184:185] op_sel_hi:[1,0]
	v_pk_mul_f32 v[66:67], v[66:67], v[184:185] op_sel_hi:[1,0]
	s_waitcnt vmcnt(5)
	v_pk_mul_f32 v[64:65], v[68:69], v[64:65]
	s_waitcnt vmcnt(3)
	v_permlane16_swap_b32_e32 v84, v86
	v_permlane16_swap_b32_e32 v85, v87
	v_lshlrev_b32_e32 v68, 16, v84
	v_and_b32_e32 v69, 0xffff0000, v84
	v_pk_mul_f32 v[60:61], v[60:61], v[184:185] op_sel_hi:[1,0]
	v_pk_mul_f32 v[44:45], v[44:45], v[184:185] op_sel_hi:[1,0]
	v_pk_mul_f32 v[64:65], v[64:65], v[68:69]
	v_pk_mul_f32 v[66:67], v[70:71], v[66:67]
	v_lshlrev_b32_e32 v68, 16, v85
	v_and_b32_e32 v69, 0xffff0000, v85
	v_pk_mul_f32 v[56:57], v[56:57], v[60:61]
	s_waitcnt vmcnt(3)
	v_lshlrev_b32_e32 v60, 16, v86
	v_and_b32_e32 v61, 0xffff0000, v86
	v_pk_mul_f32 v[48:49], v[48:49], v[184:185] op_sel_hi:[1,0]
	s_waitcnt vmcnt(0)
	v_permlane16_swap_b32_e32 v80, v82
	v_permlane16_swap_b32_e32 v81, v83
	v_pk_mul_f32 v[40:41], v[40:41], v[44:45]
	v_lshlrev_b32_e32 v44, 16, v82
	v_and_b32_e32 v45, 0xffff0000, v82
	v_pk_mul_f32 v[66:67], v[66:67], v[68:69]
	v_pk_mul_f32 v[56:57], v[56:57], v[60:61]
	v_pk_mul_f32 v[60:61], v[62:63], v[184:185] op_sel_hi:[1,0]
	v_pk_mul_f32 v[48:49], v[52:53], v[48:49]
	v_lshlrev_b32_e32 v52, 16, v80
	v_and_b32_e32 v53, 0xffff0000, v80
	v_pk_mul_f32 v[50:51], v[50:51], v[184:185] op_sel_hi:[1,0]
	v_pk_mul_f32 v[40:41], v[40:41], v[44:45]
	v_pk_mul_f32 v[44:45], v[46:47], v[184:185] op_sel_hi:[1,0]
	v_cvt_pk_bf16_f32 v64, v64, v65
	v_cvt_pk_bf16_f32 v65, v66, v67
	v_lshl_add_u64 v[66:67], v[78:79], 0, s[26:27]
	v_pk_mul_f32 v[58:59], v[58:59], v[60:61]
	v_lshlrev_b32_e32 v60, 16, v87
	v_and_b32_e32 v61, 0xffff0000, v87
	v_pk_mul_f32 v[48:49], v[48:49], v[52:53]
	v_pk_mul_f32 v[50:51], v[54:55], v[50:51]
	v_lshlrev_b32_e32 v52, 16, v81
	v_and_b32_e32 v53, 0xffff0000, v81
	v_pk_mul_f32 v[42:43], v[42:43], v[44:45]
	v_lshlrev_b32_e32 v44, 16, v83
	v_and_b32_e32 v45, 0xffff0000, v83
	s_add_u32 s26, s26, 0x20000
	v_pk_mul_f32 v[58:59], v[58:59], v[60:61]
	v_pk_mul_f32 v[50:51], v[50:51], v[52:53]
	v_pk_mul_f32 v[42:43], v[42:43], v[44:45]
	s_addc_u32 s27, s27, 0
	s_add_i32 s47, s47, 64
	v_cvt_pk_bf16_f32 v56, v56, v57
	v_cvt_pk_bf16_f32 v57, v58, v59
	v_cvt_pk_bf16_f32 v48, v48, v49
	v_cvt_pk_bf16_f32 v49, v50, v51
	v_cvt_pk_bf16_f32 v40, v40, v41
	v_cvt_pk_bf16_f32 v41, v42, v43
	s_cmp_lg_u32 s26, 0x200000
	v_mov_b32_e32 v60, v64
	v_mov_b32_e32 v61, v65
	v_mov_b32_e32 v62, v56
	v_mov_b32_e32 v63, v57
	v_mov_b32_e32 v52, v48
	v_mov_b32_e32 v53, v49
	v_mov_b32_e32 v54, v40
	v_mov_b32_e32 v55, v41
	s_nop 1
	v_permlane16_swap_b32_e32 v60, v62
	v_permlane16_swap_b32_e32 v61, v63
	v_permlane16_swap_b32_e32 v52, v54
	v_permlane16_swap_b32_e32 v53, v55
	global_store_dwordx4 v[66:67], v[60:63], off
	global_store_dwordx4 v[66:67], v[52:55], off offset:64
	s_cbranch_scc0 .LBB0_479

; #define LAS __attribute__((address_space(3)))
; __device__ __forceinline__ float bflo(unsigned u) { return __uint_as_float(u << 16); }
; __device__ __forceinline__ float bfhi(unsigned u) { return __uint_as_float(u & 0xffff0000u); }
; __device__ __forceinline__ unsigned pk2(float lo, float hi) { f32x2 v = {lo, hi}; bf2_t b = __builtin_convertvector(v, bf2_t); return __builtin_bit_cast(unsigned, b); }
; __device__ __forceinline__ float fast_rcp(float x) { return __builtin_amdgcn_rcpf(x); }
; template <bool FULL>
; __device__ __forceinline__ void hgrn_pass(int wv, const Args& a, int l, LAS unsigned char* lds, int item, bool dmy) {
;     ...
;         {
;             unsigned kt[8];
;             if (FULL) {
;                 const float El = __expf(glast - gmid);
; #pragma unroll
;                 for (int i = 0; i < 16; i += 2) {
;                     const float d0 = fmaxf(prefix + cum[i] - gmid, -80.f), d1 = fmaxf(prefix + cum[i + 1] - gmid, -80.f);
;                     const float E0 = __expf(d0), E1 = __expf(d1), R0 = fast_rcp(E0), R1 = fast_rcp(E1);
;                     const float kh0 = kk[i] * R0, kh1 = kk[i + 1] * R1;
;                     kt[i >> 1] = pk2(kh0 * El, kh1 * El);
;                     const unsigned qh = pk2(bflo(cHQ[i >> 1]) * E0, bfhi(cHQ[i >> 1]) * E1), kh = pk2(kh0, kh1);
;                     const int tA = seg * 16 + i;
;                     *(LAS bf16_t*)(lds + HG_QH + (tA * 136 + ch) * 2) = (bf16_t)(qh & 0xffffu);
;                     *(LAS bf16_t*)(lds + HG_QH + ((tA + 1) * 136 + ch) * 2) = (bf16_t)(qh >> 16);
;                     *(LAS bf16_t*)(lds + HG_KH + (tA * 136 + ch) * 2) = (bf16_t)(kh & 0xffffu);
;                     *(LAS bf16_t*)(lds + HG_KH + ((tA + 1) * 136 + ch) * 2) = (bf16_t)(kh >> 16);
;                 }
.LBB0_477:
	v_add_f32_e32 v58, 0, v58
	v_cndmask_b32_e64 v58, 0, v58, s[0:1]
	v_add_f32_e32 v59, v59, v58
	v_cndmask_b32_e64 v58, v58, v59, s[2:3]
	v_add_f32_e32 v56, v56, v58
	v_cndmask_b32_e64 v85, v58, v56, s[4:5]
	v_add_f32_e32 v56, v60, v85
	v_sub_f32_e32 v56, v56, v84
	v_add_f32_e32 v58, v61, v85
	v_max_f32_e32 v56, 0xc2a00000, v56
	v_sub_f32_e32 v58, v58, v84
	v_max_f32_e32 v59, 0xc2a00000, v58
	v_mul_f32_e32 v56, 0x3fb8aa3b, v56
	v_exp_f32_e32 v58, v56
	v_mul_f32_e32 v56, 0x3fb8aa3b, v59
	v_exp_f32_e32 v59, v56
	v_sub_f32_e32 v56, v57, v84
	v_mul_f32_e32 v60, 0x3fb8aa3b, v56
	v_rcp_f32_e32 v56, v58
	v_rcp_f32_e32 v57, v59
	v_exp_f32_e32 v60, v60
	v_pk_add_f32 v[40:41], v[40:41], 1.0 op_sel_hi:[1,0] neg_lo:[1,0] neg_hi:[1,0]
	v_lshlrev_b32_e32 v86, 16, v181
	v_pk_mul_f32 v[40:41], v[72:73], v[40:41]
	v_and_b32_e32 v87, 0xffff0000, v181
	v_pk_mul_f32 v[56:57], v[40:41], v[56:57]
	v_pk_mul_f32 v[58:59], v[58:59], v[86:87]
	v_pk_mul_f32 v[40:41], v[60:61], v[56:57] op_sel_hi:[0,1]
	v_cvt_pk_bf16_f32 v40, v40, v41
	v_cvt_pk_bf16_f32 v41, v58, v59
	v_add_f32_e32 v58, v62, v85
	v_add_f32_e32 v59, v63, v85
	v_sub_f32_e32 v58, v58, v84
	v_sub_f32_e32 v59, v59, v84
	v_max_f32_e32 v58, 0xc2a00000, v58
	v_max_f32_e32 v59, 0xc2a00000, v59
	v_mul_f32_e32 v58, 0x3fb8aa3b, v58
	v_mul_f32_e32 v59, 0x3fb8aa3b, v59
	v_exp_f32_e32 v58, v58
	v_exp_f32_e32 v59, v59
	v_cvt_pk_bf16_f32 v61, v56, v57
	v_pk_add_f32 v[42:43], v[42:43], 1.0 op_sel_hi:[1,0] neg_lo:[1,0] neg_hi:[1,0]
	v_rcp_f32_e32 v56, v58
	v_rcp_f32_e32 v57, v59
	v_pk_mul_f32 v[42:43], v[72:73], v[42:43]
	ds_write_b16 v119, v41
	ds_write_b16_d16_hi v120, v41
	ds_write_b16 v119, v61 offset:17408
	ds_write_b16_d16_hi v120, v61 offset:17408
	v_pk_mul_f32 v[42:43], v[42:43], v[56:57]
	v_pk_add_f32 v[44:45], v[44:45], 1.0 op_sel_hi:[1,0] neg_lo:[1,0] neg_hi:[1,0]
	v_pk_mul_f32 v[56:57], v[60:61], v[42:43] op_sel_hi:[0,1]
	v_cvt_pk_bf16_f32 v41, v56, v57
	v_lshlrev_b32_e32 v56, 16, v180
	v_and_b32_e32 v57, 0xffff0000, v180
	v_pk_mul_f32 v[56:57], v[58:59], v[56:57]
	v_cvt_pk_bf16_f32 v59, v42, v43
	v_cvt_pk_bf16_f32 v58, v56, v57
	v_add_f32_e32 v56, v64, v85
	v_add_f32_e32 v57, v65, v85
	v_sub_f32_e32 v56, v56, v84
	v_sub_f32_e32 v57, v57, v84
	v_max_f32_e32 v56, 0xc2a00000, v56
	v_max_f32_e32 v57, 0xc2a00000, v57
	v_mul_f32_e32 v56, 0x3fb8aa3b, v56
	v_mul_f32_e32 v57, 0x3fb8aa3b, v57
	v_exp_f32_e32 v56, v56
	v_exp_f32_e32 v57, v57
	v_pk_mul_f32 v[44:45], v[72:73], v[44:45]
	ds_write_b16 v121, v58
	v_rcp_f32_e32 v42, v56
	v_rcp_f32_e32 v43, v57
	ds_write_b16_d16_hi v122, v58
	ds_write_b16 v121, v59 offset:17408
	ds_write_b16_d16_hi v122, v59 offset:17408
	v_lshlrev_b32_e32 v58, 16, v179
	v_and_b32_e32 v59, 0xffff0000, v179
	v_pk_mul_f32 v[44:45], v[44:45], v[42:43]
	v_pk_mul_f32 v[56:57], v[56:57], v[58:59]
	v_pk_mul_f32 v[42:43], v[60:61], v[44:45] op_sel_hi:[0,1]
	v_cvt_pk_bf16_f32 v42, v42, v43
	v_cvt_pk_bf16_f32 v43, v56, v57
	v_add_f32_e32 v56, v66, v85
	v_add_f32_e32 v57, v67, v85
	v_sub_f32_e32 v56, v56, v84
	v_sub_f32_e32 v57, v57, v84
	v_max_f32_e32 v56, 0xc2a00000, v56
	v_max_f32_e32 v57, 0xc2a00000, v57
	v_mul_f32_e32 v56, 0x3fb8aa3b, v56
	v_mul_f32_e32 v57, 0x3fb8aa3b, v57
	v_exp_f32_e32 v56, v56
	v_exp_f32_e32 v57, v57
	v_cvt_pk_bf16_f32 v58, v44, v45
	v_pk_add_f32 v[46:47], v[46:47], 1.0 op_sel_hi:[1,0] neg_lo:[1,0] neg_hi:[1,0]
	v_rcp_f32_e32 v44, v56
	v_rcp_f32_e32 v45, v57
	v_pk_mul_f32 v[46:47], v[72:73], v[46:47]
	ds_write_b16 v123, v43
	ds_write_b16_d16_hi v124, v43
	ds_write_b16 v123, v58 offset:17408
	ds_write_b16_d16_hi v124, v58 offset:17408
	v_pk_mul_f32 v[44:45], v[46:47], v[44:45]
	v_pk_add_f32 v[48:49], v[48:49], 1.0 op_sel_hi:[1,0] neg_lo:[1,0] neg_hi:[1,0]
	v_pk_mul_f32 v[46:47], v[60:61], v[44:45] op_sel_hi:[0,1]
	v_cvt_pk_bf16_f32 v43, v46, v47
	v_lshlrev_b32_e32 v46, 16, v178
	v_and_b32_e32 v47, 0xffff0000, v178
	v_pk_mul_f32 v[46:47], v[56:57], v[46:47]
	v_cvt_pk_bf16_f32 v57, v44, v45
	v_cvt_pk_bf16_f32 v56, v46, v47
	v_add_f32_e32 v46, v68, v85
	v_add_f32_e32 v47, v69, v85
	v_sub_f32_e32 v46, v46, v84
	v_sub_f32_e32 v47, v47, v84
	v_max_f32_e32 v46, 0xc2a00000, v46
	v_max_f32_e32 v47, 0xc2a00000, v47
	v_mul_f32_e32 v46, 0x3fb8aa3b, v46
	v_mul_f32_e32 v47, 0x3fb8aa3b, v47
	v_exp_f32_e32 v46, v46
	v_exp_f32_e32 v47, v47
	v_pk_mul_f32 v[48:49], v[72:73], v[48:49]
	ds_write_b16 v125, v56
	v_rcp_f32_e32 v44, v46
	v_rcp_f32_e32 v45, v47
	ds_write_b16_d16_hi v126, v56
	ds_write_b16 v125, v57 offset:17408
	ds_write_b16_d16_hi v126, v57 offset:17408
	v_lshlrev_b32_e32 v56, 16, v177
	v_and_b32_e32 v57, 0xffff0000, v177
	v_pk_mul_f32 v[48:49], v[48:49], v[44:45]
	v_pk_mul_f32 v[46:47], v[46:47], v[56:57]
	v_pk_mul_f32 v[44:45], v[60:61], v[48:49] op_sel_hi:[0,1]
	v_cvt_pk_bf16_f32 v44, v44, v45
	v_cvt_pk_bf16_f32 v45, v46, v47
	v_add_f32_e32 v46, v70, v85
	v_add_f32_e32 v47, v71, v85
	v_sub_f32_e32 v46, v46, v84
	v_sub_f32_e32 v47, v47, v84
	v_max_f32_e32 v46, 0xc2a00000, v46
	v_max_f32_e32 v47, 0xc2a00000, v47
	v_mul_f32_e32 v46, 0x3fb8aa3b, v46
	v_mul_f32_e32 v47, 0x3fb8aa3b, v47
	v_exp_f32_e32 v46, v46
	v_exp_f32_e32 v47, v47
	v_cvt_pk_bf16_f32 v56, v48, v49
	v_pk_add_f32 v[50:51], v[50:51], 1.0 op_sel_hi:[1,0] neg_lo:[1,0] neg_hi:[1,0]
	v_rcp_f32_e32 v48, v46
	v_rcp_f32_e32 v49, v47
	v_pk_mul_f32 v[50:51], v[72:73], v[50:51]
	ds_write_b16 v127, v45
	ds_write_b16_d16_hi v128, v45
	ds_write_b16 v127, v56 offset:17408
	ds_write_b16_d16_hi v128, v56 offset:17408
	v_pk_mul_f32 v[48:49], v[50:51], v[48:49]
	v_pk_add_f32 v[52:53], v[52:53], 1.0 op_sel_hi:[1,0] neg_lo:[1,0] neg_hi:[1,0]
	v_pk_mul_f32 v[50:51], v[60:61], v[48:49] op_sel_hi:[0,1]
	v_cvt_pk_bf16_f32 v45, v50, v51
; #define LAS __attribute__((address_space(3)))
; template <bool FULL>
; __device__ __forceinline__ void hgrn_pass(int wv, const Args& a, int l, LAS unsigned char* lds, int item, bool dmy) {
;     ...
;             LAS u32x4* kp = (LAS u32x4*)(lds + HG_KTT + (ch * 72 + seg * 16) * 2); LAS u32x4* vp = (LAS u32x4*)(lds + HG_VTT + (ch * 72 + seg * 16) * 2);
;             kp[0] = (u32x4){kt[0], kt[1], kt[2], kt[3]}; kp[1] = (u32x4){kt[4], kt[5], kt[6], kt[7]};
;             vp[0] = (u32x4){cHI[0], cHI[1], cHI[2], cHI[3]}; vp[1] = (u32x4){cHI[4], cHI[5], cHI[6], cHI[7]};
;         }
;         __syncthreads();
;         f32x4 oacc[4]; f32x4 gn[4]; u32x2 cHG[4];
;         if (FULL) {
;             {
;                 const f32x4 em = *(const LAS f32x4*)(lds + HG_EM + (wid * 16 + 4 * fq) * 4);
; #pragma unroll
;                 for (int j = 0; j < 8; ++j) { u32x2 w; w.x = pk2(sacc[j][0] * em[0], sacc[j][1] * em[1]); w.y = pk2(sacc[j][2] * em[2], sacc[j][3] * em[3]); *(LAS u32x2*)(lds + HG_ST + ((j * 16 + fr) * 136 + wid * 16 + 4 * fq) * 2) = w; }
;             }
;             {
;                 const int tiA = wid >> 1;
; #pragma unroll
;                 for (int q = 0; q < 2; ++q) {
;                     const int sj = (wid & 1) * 2 + q;
;                     f32x4 ac = (f32x4){0.f, 0.f, 0.f, 0.f};
; #pragma unroll
;                     for (int k4 = 0; k4 < 4; ++k4) {
;                         const bf16x8 av = lds_ld16(lds + HG_QH + ((tiA * 16 + fr) * 136 + k4 * 32 + 8 * fq) * 2);
;                         const bf16x8 bv = lds_ld16(lds + HG_KH + ((sj * 16 + fr) * 136 + k4 * 32 + 8 * fq) * 2);
;                         ac = mfma16(av, bv, ac);
;                     }
;                     const int s = sj * 16 + fr, tb0 = tiA * 16 + 4 * fq;
;                     const unsigned w0 = pk2(s <= tb0 ? ac[0] : 0.f, s <= tb0 + 1 ? ac[1] : 0.f), w1 = pk2(s <= tb0 + 2 ? ac[2] : 0.f, s <= tb0 + 3 ? ac[3] : 0.f);
;                     *(LAS bf16_t*)(lds + HG_AM + ((tb0 + 0) * 72 + s) * 2) = (bf16_t)(w0 & 0xffffu);
;                     *(LAS bf16_t*)(lds + HG_AM + ((tb0 + 1) * 72 + s) * 2) = (bf16_t)(w0 >> 16);
;                     *(LAS bf16_t*)(lds + HG_AM + ((tb0 + 2) * 72 + s) * 2) = (bf16_t)(w1 & 0xffffu);
;                     *(LAS bf16_t*)(lds + HG_AM + ((tb0 + 3) * 72 + s) * 2) = (bf16_t)(w1 >> 16);
;                 }
;             }
;             __syncthreads();
	v_lshlrev_b32_e32 v50, 16, v176
	v_and_b32_e32 v51, 0xffff0000, v176
	v_pk_mul_f32 v[46:47], v[46:47], v[50:51]
	v_pk_mul_f32 v[52:53], v[72:73], v[52:53]
	v_cvt_pk_bf16_f32 v56, v46, v47
	v_add_f32_e32 v46, v80, v85
	v_sub_f32_e32 v46, v46, v84
	v_add_f32_e32 v47, v81, v85
	v_max_f32_e32 v46, 0xc2a00000, v46
	v_sub_f32_e32 v47, v47, v84
	v_max_f32_e32 v47, 0xc2a00000, v47
	v_mul_f32_e32 v46, 0x3fb8aa3b, v46
	v_exp_f32_e32 v50, v46
	v_mul_f32_e32 v46, 0x3fb8aa3b, v47
	v_exp_f32_e32 v51, v46
	v_cvt_pk_bf16_f32 v48, v48, v49
	v_rcp_f32_e32 v46, v50
	ds_write_b16 v129, v56
	v_rcp_f32_e32 v47, v51
	ds_write_b16_d16_hi v130, v56
	ds_write_b16 v129, v48 offset:17408
	ds_write_b16_d16_hi v130, v48 offset:17408
	v_pk_add_f32 v[54:55], v[54:55], 1.0 op_sel_hi:[1,0] neg_lo:[1,0] neg_hi:[1,0]
	s_add_i32 s95, 0, 0x18000
	v_pk_mul_f32 v[48:49], v[52:53], v[46:47]
	v_lshlrev_b32_e32 v52, 16, v175
	v_and_b32_e32 v53, 0xffff0000, v175
	v_pk_mul_f32 v[46:47], v[60:61], v[48:49] op_sel_hi:[0,1]
	v_pk_mul_f32 v[50:51], v[50:51], v[52:53]
	v_cvt_pk_bf16_f32 v46, v46, v47
	v_cvt_pk_bf16_f32 v47, v50, v51
	v_add_f32_e32 v50, v82, v85
	v_add_f32_e32 v51, v83, v85
	v_sub_f32_e32 v50, v50, v84
	v_sub_f32_e32 v51, v51, v84
	v_max_f32_e32 v50, 0xc2a00000, v50
	v_max_f32_e32 v51, 0xc2a00000, v51
	v_mul_f32_e32 v50, 0x3fb8aa3b, v50
	v_mul_f32_e32 v51, 0x3fb8aa3b, v51
	v_exp_f32_e32 v50, v50
	v_exp_f32_e32 v51, v51
	v_cvt_pk_bf16_f32 v52, v48, v49
	v_pk_mul_f32 v[54:55], v[72:73], v[54:55]
	v_rcp_f32_e32 v48, v50
	v_rcp_f32_e32 v49, v51
	ds_write_b16 v131, v47
	ds_write_b16_d16_hi v132, v47
	ds_write_b16 v131, v52 offset:17408
	ds_write_b16_d16_hi v132, v52 offset:17408
	v_lshl_add_u64 v[80:81], v[76:77], 0, s[26:27]
	v_pk_mul_f32 v[48:49], v[54:55], v[48:49]
	s_nop 0
	v_pk_mul_f32 v[52:53], v[60:61], v[48:49] op_sel_hi:[0,1]
	v_cvt_pk_bf16_f32 v47, v52, v53
	v_lshlrev_b32_e32 v52, 16, v174
	v_and_b32_e32 v53, 0xffff0000, v174
	v_pk_mul_f32 v[50:51], v[50:51], v[52:53]
	v_cvt_pk_bf16_f32 v48, v48, v49
	v_cvt_pk_bf16_f32 v50, v50, v51
	ds_write_b16 v133, v50
	ds_write_b16_d16_hi v134, v50
	ds_write_b16 v133, v48 offset:17408
	ds_write_b16_d16_hi v134, v48 offset:17408
	v_add_u32_e32 v48, 0, v91
	ds_write_b128 v48, v[40:43] offset:52224
	ds_write_b128 v48, v[44:47] offset:52240
	v_add_u32_e32 v40, s71, v91
	ds_write_b128 v40, v[32:35]
	ds_write_b128 v40, v[36:39] offset:16
	s_waitcnt lgkmcnt(0)
	s_barrier
	ds_read_b128 v[32:35], v149 offset:34816
	v_add_u32_e32 v48, 0, v100
	s_waitcnt lgkmcnt(0)
	v_pk_mul_f32 v[36:37], v[2:3], v[34:35]
	v_pk_mul_f32 v[38:39], v[0:1], v[32:33]
	s_nop 0
	v_cvt_pk_bf16_f32 v38, v38, v39
	v_cvt_pk_bf16_f32 v39, v36, v37
	v_add_u32_e32 v36, s95, v97
	ds_write_b64 v36, v[38:39]
	v_pk_mul_f32 v[36:37], v[6:7], v[34:35]
	v_pk_mul_f32 v[38:39], v[4:5], v[32:33]
	s_nop 0
	v_cvt_pk_bf16_f32 v38, v38, v39
	v_cvt_pk_bf16_f32 v39, v36, v37
	v_add_u32_e32 v36, 0x1100, v97
	v_add_u32_e32 v36, s95, v36
	ds_write_b64 v36, v[38:39]
	v_pk_mul_f32 v[36:37], v[10:11], v[34:35]
	v_pk_mul_f32 v[38:39], v[8:9], v[32:33]
	s_nop 0
	v_cvt_pk_bf16_f32 v38, v38, v39
	v_cvt_pk_bf16_f32 v39, v36, v37
	v_add_u32_e32 v36, 0x2200, v97
	v_add_u32_e32 v36, s95, v36
	ds_write_b64 v36, v[38:39]
	v_pk_mul_f32 v[36:37], v[14:15], v[34:35]
	v_pk_mul_f32 v[38:39], v[12:13], v[32:33]
	s_nop 0
	v_cvt_pk_bf16_f32 v38, v38, v39
	v_cvt_pk_bf16_f32 v39, v36, v37
	v_add_u32_e32 v36, 0x3300, v97
	v_add_u32_e32 v36, s95, v36
	ds_write_b64 v36, v[38:39]
	v_pk_mul_f32 v[36:37], v[18:19], v[34:35]
	v_pk_mul_f32 v[38:39], v[16:17], v[32:33]
	s_nop 0
	v_cvt_pk_bf16_f32 v38, v38, v39
	v_cvt_pk_bf16_f32 v39, v36, v37
	v_add_u32_e32 v36, 0x4400, v97
	v_add_u32_e32 v36, s95, v36
	ds_write_b64 v36, v[38:39]
	v_pk_mul_f32 v[36:37], v[22:23], v[34:35]
	v_pk_mul_f32 v[38:39], v[20:21], v[32:33]
	s_nop 0
	v_cvt_pk_bf16_f32 v38, v38, v39
	v_cvt_pk_bf16_f32 v39, v36, v37
	v_add_u32_e32 v36, 0x5500, v97
	v_add_u32_e32 v36, s95, v36
	ds_write_b64 v36, v[38:39]
	v_pk_mul_f32 v[36:37], v[26:27], v[34:35]
	v_pk_mul_f32 v[38:39], v[24:25], v[32:33]
	v_pk_mul_f32 v[34:35], v[30:31], v[34:35]
	v_pk_mul_f32 v[32:33], v[28:29], v[32:33]
	v_cvt_pk_bf16_f32 v38, v38, v39
	v_cvt_pk_bf16_f32 v39, v36, v37
	v_add_u32_e32 v36, s95, v98
	v_cvt_pk_bf16_f32 v32, v32, v33
	v_cvt_pk_bf16_f32 v33, v34, v35
	v_add_u32_e32 v34, s95, v99
	ds_write_b64 v36, v[38:39]
	ds_write_b64 v34, v[32:33]
	ds_read_b128 v[32:35], v135
	ds_read_b128 v[36:39], v135 offset:64
	ds_read_b128 v[40:43], v48 offset:17408
	ds_read_b128 v[44:47], v48 offset:17472
	s_waitcnt lgkmcnt(1)
	v_mfma_f32_16x16x32_bf16 v[32:35], v[32:35], v[40:43], 0
	ds_read_b128 v[40:43], v135 offset:128
	s_waitcnt lgkmcnt(1)
	v_mfma_f32_16x16x32_bf16 v[32:35], v[36:39], v[44:47], v[32:35]
	ds_read_b128 v[36:39], v135 offset:192
	ds_read_b128 v[44:47], v48 offset:17536
	ds_read_b128 v[48:51], v48 offset:17600
	s_waitcnt lgkmcnt(1)
	v_mfma_f32_16x16x32_bf16 v[32:35], v[40:43], v[44:47], v[32:35]
	s_waitcnt lgkmcnt(0)
	v_mfma_f32_16x16x32_bf16 v[32:35], v[36:39], v[48:51], v[32:35]
	s_nop 7
	v_cndmask_b32_e64 v32, v32, 0, s[8:9]
	v_cndmask_b32_e64 v33, v33, 0, s[10:11]
	v_cvt_pk_bf16_f32 v32, v32, v33
	v_cndmask_b32_e64 v33, v34, 0, s[12:13]
	v_cndmask_b32_e64 v34, v35, 0, s[14:15]
	v_cvt_pk_bf16_f32 v33, v33, v34
	ds_write_b16 v136, v32
	ds_write_b16_d16_hi v137, v32
	ds_write_b16 v138, v33
	ds_write_b16_d16_hi v139, v33
	ds_read_b128 v[32:35], v135
	ds_read_b128 v[36:39], v135 offset:64
	ds_read_b128 v[40:43], v140 offset:17408
	ds_read_b128 v[44:47], v140 offset:17472
	s_waitcnt lgkmcnt(1)
	v_mfma_f32_16x16x32_bf16 v[32:35], v[32:35], v[40:43], 0
	ds_read_b128 v[40:43], v135 offset:128
	s_waitcnt lgkmcnt(1)
	v_mfma_f32_16x16x32_bf16 v[32:35], v[36:39], v[44:47], v[32:35]
	ds_read_b128 v[36:39], v135 offset:192
	ds_read_b128 v[44:47], v140 offset:17536
	ds_read_b128 v[48:51], v140 offset:17600
	s_waitcnt lgkmcnt(1)
	v_mfma_f32_16x16x32_bf16 v[32:35], v[40:43], v[44:47], v[32:35]
	s_waitcnt lgkmcnt(0)
	v_mfma_f32_16x16x32_bf16 v[32:35], v[36:39], v[48:51], v[32:35]
	s_nop 7
	v_cndmask_b32_e64 v32, v32, 0, s[16:17]
	v_cndmask_b32_e64 v33, v33, 0, s[18:19]
	v_cvt_pk_bf16_f32 v32, v32, v33
	v_cndmask_b32_e64 v33, v34, 0, s[20:21]
	v_cndmask_b32_e64 v34, v35, 0, s[22:23]
	v_cvt_pk_bf16_f32 v33, v33, v34
	ds_write_b16 v141, v32
	ds_write_b16_d16_hi v142, v32
	ds_write_b16 v143, v33
	ds_write_b16_d16_hi v144, v33
	s_waitcnt lgkmcnt(0)
	s_barrier
; __device__ __forceinline__ float shx(float v, int lane, int mask) { return __int_as_float(__builtin_amdgcn_ds_bpermute((lane ^ mask) << 2, __float_as_int(v))); }
; __device__ __forceinline__ f32x4 mfma16(bf16x8 a, bf16x8 b, f32x4 c) { return __builtin_amdgcn_mfma_f32_16x16x32_bf16(a, b, c, 0, 0, 0); }
; template <bool FULL>
; __device__ __forceinline__ void hgrn_pass(int wv, const Args& a, int l, LAS unsigned char* lds, int item, bool dmy) {
;     ...
;             { const size_t or_ = row_base + (size_t)c * 64 + ti * 16 + fr;
; #pragma unroll
;               for (int jj = 0; jj < 4; ++jj) { cHG[jj] = *(const u32x2*)(HGt + or_ * DM + h * 128 + (dvh * 4 + jj) * 16 + 4 * fq); gn[jj] = *(const f32x4*)(a.in[7] + l * DM + h * 128 + (dvh * 4 + jj) * 16 + 4 * fq); } }
; #pragma unroll
;             for (int jj = 0; jj < 4; ++jj) oacc[jj] = (f32x4){0.f, 0.f, 0.f, 0.f};
; #pragma unroll
;             for (int k2 = 0; k2 < 2; ++k2) {
;                 const bf16x8 bv = lds_ld16(lds + HG_AM + ((ti * 16 + fr) * 72 + k2 * 32 + 8 * fq) * 2);
; #pragma unroll
;                 for (int jj = 0; jj < 4; ++jj) { const bf16x8 av = lds_ld16(lds + HG_VTT + (((dvh * 4 + jj) * 16 + fr) * 72 + k2 * 32 + 8 * fq) * 2); oacc[jj] = mfma16(av, bv, oacc[jj]); }
;             }
; #pragma unroll
;             for (int k4 = 0; k4 < 4; ++k4) {
;                 const bf16x8 bv = lds_ld16(lds + HG_QH + ((ti * 16 + fr) * 136 + k4 * 32 + 8 * fq) * 2);
; #pragma unroll
;                 for (int jj = 0; jj < 4; ++jj) { const bf16x8 av = lds_ld16(lds + HG_ST + (((dvh * 4 + jj) * 16 + fr) * 136 + k4 * 32 + 8 * fq) * 2); oacc[jj] = mfma16(av, bv, oacc[jj]); }
;             }
;             float s = 0.f;
; #pragma unroll
;             for (int jj = 0; jj < 4; ++jj) s += (oacc[jj][0] * oacc[jj][0] + oacc[jj][1] * oacc[jj][1]) + (oacc[jj][2] * oacc[jj][2] + oacc[jj][3] * oacc[jj][3]);
;             s += shx(s, LANE_, 16); s += shx(s, LANE_, 32);
;             if (fq == 0) SSQP[dvh * 64 + ti * 16 + fr] = s;
	ds_read_b128 v[32:35], v150
	ds_read_b128 v[36:39], v151
	ds_read_b128 v[40:43], v145
	ds_read_b128 v[44:47], v145 offset:64
	ds_read_b128 v[48:51], v152
	ds_read_b128 v[56:59], v154
	s_waitcnt lgkmcnt(3)
	v_mfma_f32_16x16x32_bf16 v[32:35], v[32:35], v[40:43], 0
	ds_read_b128 v[52:55], v153
	s_waitcnt lgkmcnt(1)
	v_mfma_f32_16x16x32_bf16 v[32:35], v[56:59], v[44:47], v[32:35]
	ds_read_b128 v[56:59], v156
	v_mfma_f32_16x16x32_bf16 v[48:51], v[48:51], v[40:43], 0
	s_waitcnt lgkmcnt(0)
	v_mfma_f32_16x16x32_bf16 v[48:51], v[56:59], v[44:47], v[48:51]
	v_add_u32_e32 v56, s95, v101
	ds_read_b128 v[56:59], v56
	v_mfma_f32_16x16x32_bf16 v[36:39], v[36:39], v[40:43], 0
	v_mfma_f32_16x16x32_bf16 v[40:43], v[52:55], v[40:43], 0
	ds_read_b128 v[52:55], v155
	s_waitcnt lgkmcnt(0)
	v_mfma_f32_16x16x32_bf16 v[36:39], v[52:55], v[44:47], v[36:39]
	ds_read_b128 v[52:55], v157
	s_waitcnt lgkmcnt(0)
	v_mfma_f32_16x16x32_bf16 v[40:43], v[52:55], v[44:47], v[40:43]
	v_add_u32_e32 v44, s95, v102
	ds_read_b128 v[44:47], v44
	ds_read_b128 v[52:55], v146
	ds_read_b128 v[60:63], v146 offset:64
	s_waitcnt lgkmcnt(1)
	v_mfma_f32_16x16x32_bf16 v[32:35], v[56:59], v[52:55], v[32:35]
	v_add_u32_e32 v56, s95, v103
	ds_read_b128 v[56:59], v56
	v_mfma_f32_16x16x32_bf16 v[36:39], v[44:47], v[52:55], v[36:39]
	v_add_u32_e32 v44, s95, v104
	ds_read_b128 v[44:47], v44
	s_waitcnt lgkmcnt(0)
	v_mfma_f32_16x16x32_bf16 v[40:43], v[44:47], v[52:55], v[40:43]
	v_add_u32_e32 v44, s95, v106
	ds_read_b128 v[44:47], v44
	v_mfma_f32_16x16x32_bf16 v[48:51], v[56:59], v[52:55], v[48:51]
	v_add_u32_e32 v52, s95, v107
	ds_read_b128 v[52:55], v52
	v_add_u32_e32 v56, s95, v105
	s_waitcnt lgkmcnt(1)
	v_mfma_f32_16x16x32_bf16 v[36:39], v[44:47], v[60:63], v[36:39]
	v_add_u32_e32 v44, s95, v108
	ds_read_b128 v[44:47], v44
	ds_read_b128 v[56:59], v56
	s_waitcnt lgkmcnt(2)
	v_mfma_f32_16x16x32_bf16 v[48:51], v[52:55], v[60:63], v[48:51]
	v_add_u32_e32 v52, s95, v109
	ds_read_b128 v[52:55], v52
	s_waitcnt lgkmcnt(2)
	v_mfma_f32_16x16x32_bf16 v[40:43], v[44:47], v[60:63], v[40:43]
	ds_read_b128 v[44:47], v146 offset:128
	s_waitcnt lgkmcnt(2)
	v_mfma_f32_16x16x32_bf16 v[32:35], v[56:59], v[60:63], v[32:35]
	v_add_u32_e32 v56, s95, v110
	ds_read_b128 v[56:59], v56
	ds_read_b128 v[174:177], v146 offset:192
	s_waitcnt lgkmcnt(2)
	v_mfma_f32_16x16x32_bf16 v[32:35], v[52:55], v[44:47], v[32:35]
	v_add_u32_e32 v52, s95, v111
	ds_read_b128 v[52:55], v52
	s_waitcnt lgkmcnt(2)
	v_mfma_f32_16x16x32_bf16 v[36:39], v[56:59], v[44:47], v[36:39]
	v_add_u32_e32 v56, s95, v112
	ds_read_b128 v[56:59], v56
	s_waitcnt lgkmcnt(1)
	v_mfma_f32_16x16x32_bf16 v[48:51], v[52:55], v[44:47], v[48:51]
	v_add_u32_e32 v52, s95, v113
	ds_read_b128 v[52:55], v52
	s_waitcnt lgkmcnt(1)
	v_mfma_f32_16x16x32_bf16 v[44:47], v[56:59], v[44:47], v[40:43]
	s_nop 2
	v_add_u32_e32 v40, s95, v114
	ds_read_b128 v[40:43], v40
	s_waitcnt lgkmcnt(1)
	v_mfma_f32_16x16x32_bf16 v[64:67], v[52:55], v[174:177], v[32:35]
	s_nop 2
	v_add_u32_e32 v32, s95, v115
	ds_read_b128 v[32:35], v32
	global_load_dwordx4 v[68:71], v[74:75], off
	global_load_dwordx4 v[56:59], v[74:75], off offset:64
	global_load_dwordx4 v[84:87], v[80:81], off offset:-64
	s_nop 0
	global_load_dwordx4 v[80:83], v[80:81], off
	s_waitcnt lgkmcnt(1)
	v_mfma_f32_16x16x32_bf16 v[60:63], v[40:43], v[174:177], v[36:39]
	s_nop 2
	v_add_u32_e32 v36, s95, v116
	ds_read_b128 v[36:39], v36
	global_load_dwordx4 v[52:55], v[74:75], off offset:128
	global_load_dwordx4 v[40:43], v[74:75], off offset:192
	s_waitcnt lgkmcnt(1)
	v_mfma_f32_16x16x32_bf16 v[48:51], v[32:35], v[174:177], v[48:51]
	v_mul_f32_e32 v32, v65, v65
	v_mul_f32_e32 v33, v67, v67
	v_fmac_f32_e32 v32, v64, v64
	v_fmac_f32_e32 v33, v66, v66
	v_add_f32_e32 v32, v32, v33
	v_mul_f32_e32 v33, v61, v61
	v_mul_f32_e32 v34, v63, v63
	v_fmac_f32_e32 v33, v60, v60
	v_fmac_f32_e32 v34, v62, v62
	s_waitcnt lgkmcnt(0)
	v_mfma_f32_16x16x32_bf16 v[44:47], v[36:39], v[174:177], v[44:47]
	v_add_f32_e32 v33, v33, v34
	v_add_f32_e32 v32, v32, v33
	v_mul_f32_e32 v33, v49, v49
	v_mul_f32_e32 v34, v51, v51
	v_fmac_f32_e32 v33, v48, v48
	v_fmac_f32_e32 v34, v50, v50
	v_add_f32_e32 v33, v33, v34
	v_add_f32_e32 v32, v32, v33
	v_mul_f32_e32 v33, v45, v45
	v_mul_f32_e32 v34, v47, v47
	v_fmac_f32_e32 v33, v44, v44
	v_fmac_f32_e32 v34, v46, v46
	v_add_f32_e32 v33, v33, v34
	v_add_f32_e32 v32, v32, v33
	ds_bpermute_b32 v33, v92, v32
	s_waitcnt lgkmcnt(0)
	v_add_f32_e32 v32, v32, v33
	ds_bpermute_b32 v33, v93, v32
	s_and_saveexec_b64 s[24:25], s[6:7]
	s_cbranch_execz .LBB0_474
	s_waitcnt lgkmcnt(0)
	v_add_f32_e32 v32, v32, v33
	ds_write_b32 v147, v32
	s_branch .LBB0_474
